# m10 minus the 8 redundant post-barrier s_waitcnt lgkmcnt(0) in the GEMM K-loop (the pre-barrier wait already drains LDS)
# speedup vs baseline: 1.0051x; 1.0051x over previous
; #define PG8_STAGE(bufoff, gbase, voff) do { _Pragma("unroll") for (int _i = 0; _i < 2; ++_i) \
;         __builtin_amdgcn_global_load_lds((const unsigned*)((const char*)(gbase) + (voff)[_i]), (LAS unsigned*)(lds + (bufoff) + ldsw + _i * 8192), 16, 0, 0); } while (0)
; #define PG8_LDA(dst, b, h) do { _Pragma("unroll") for (int m = 0; m < 4; ++m) _Pragma("unroll") for (int k = 0; k < 2; ++k) dst[m][k] = *(const LAS bf16x8*)(lds + PG8_SA(b, h) + aoff + m * 2048 + k * 1024); } while (0)
; #define PG8_LDB(dst, b, h) do { _Pragma("unroll") for (int n = 0; n < 2; ++n) _Pragma("unroll") for (int k = 0; k < 2; ++k) dst[n][k] = *(const LAS bf16x8*)(lds + PG8_SB(b, h) + boff + n * 2048 + k * 1024); } while (0)
; #define PG8_MMA(ai, bj, At, Bt) do { __builtin_amdgcn_s_setprio(1); _Pragma("unroll") for (int m = 0; m < 4; ++m) _Pragma("unroll") for (int n = 0; n < 2; ++n) _Pragma("unroll") for (int k = 0; k < 2; ++k) \
;         acc[ai][bj][m][n] = __builtin_amdgcn_mfma_f32_16x16x32_bf16(Bt[n][k], At[m][k], acc[ai][bj][m][n], 0, 0, 0); __builtin_amdgcn_s_setprio(0); } while (0)
; #define PG8_WAIT_V(n) asm volatile("s_waitcnt vmcnt(" #n ")" ::: "memory")
; #define PG8_WAIT_L(n) asm volatile("s_waitcnt lgkmcnt(" #n ")" ::: "memory")
; #define PG8_BAR __builtin_amdgcn_s_barrier()
; #define PG8_SCHED __builtin_amdgcn_sched_barrier(0)
; __device__ __forceinline__ void gemm_phase(LAS unsigned char* lds, const GP p, const int tid) {
;     ...
;             const char* a1 = cA + (size_t)(t + 1) * kstep;
;             const char* a2 = last ? nA : cA + (size_t)(t + 2) * kstep; const char* b2 = last ? nB : cB + (size_t)(t + 2) * kstep;
;             const char* a3 = a2 + kstep; const char* b3 = b2 + kstep;
;             PG8_LDB(B0, 0, 0); PG8_LDB(B1, 0, 1); PG8_SCHED; PG8_LDA(At, 0, 0); PG8_STAGE(PG8_SA(1, 1), a1 + hstep, voffA);
;             PG8_WAIT_V(8); PG8_WAIT_L(0); PG8_BAR; PG8_MMA(0, 0, At, B0); PG8_MMA(0, 1, At, B1); PG8_BAR; PG8_SCHED;
;             PG8_LDA(At, 0, 1); PG8_STAGE(PG8_SB(0, 0), b2, voffB); PG8_STAGE(PG8_SB(0, 1), b2 + hstep, voffB); PG8_STAGE(PG8_SA(0, 0), a2, voffA);
;             PG8_WAIT_V(8); PG8_WAIT_L(0); PG8_BAR; PG8_MMA(1, 0, At, B0); PG8_MMA(1, 1, At, B1); PG8_BAR; PG8_SCHED;
.Lpeel_body:
	s_add_i32 s98, s98, 2
	s_add_u32 s43, s82, 0x80
	s_addc_u32 s99, s83, 0
	s_and_b64 s[86:87], s[84:85], exec
	s_cselect_b32 s87, s77, s99
	s_cselect_b32 s86, s76, s43
	s_add_i32 s43, 0, 0x10000
	s_and_b64 s[84:85], s[84:85], exec
	s_cselect_b32 s85, s79, s91
	s_cselect_b32 s84, s78, s81
	s_add_i32 s99, 0, 0x14000
	ds_read_b128 v[130:133], v238
	ds_read_b128 v[134:137], v238 offset:1024
	ds_read_b128 v[138:141], v238 offset:2048
	ds_read_b128 v[180:183], v238 offset:3072
	ds_read_b128 v[184:187], v239
	ds_read_b128 v[188:191], v239 offset:1024
	ds_read_b128 v[192:195], v239 offset:2048
	ds_read_b128 v[196:199], v239 offset:3072
	s_add_i32 m0, s53, 0xc000
	ds_read_b128 v[200:203], v167
	ds_read_b128 v[204:207], v167 offset:1024
	ds_read_b128 v[208:211], v167 offset:2048
	ds_read_b128 v[218:221], v167 offset:3072
	ds_read_b128 v[222:225], v167 offset:4096
	ds_read_b128 v[226:229], v167 offset:5120
	ds_read_b128 v[230:233], v167 offset:6144
	ds_read_b128 v[234:237], v167 offset:7168
	global_load_lds_dwordx4 v160, s[82:83]
	s_add_i32 m0, s53, 0xe000
	s_nop 0
	global_load_lds_dwordx4 v162, s[82:83]
	s_waitcnt vmcnt(8)
	s_waitcnt lgkmcnt(0)
	s_barrier
	s_setprio 1
	v_mfma_f32_16x16x32_bf16 v[124:127], v[130:133], v[200:203], 0
	v_mfma_f32_16x16x32_bf16 v[120:123], v[138:141], v[200:203], 0
	v_mfma_f32_16x16x32_bf16 v[108:111], v[130:133], v[208:211], 0
	v_mfma_f32_16x16x32_bf16 v[104:107], v[138:141], v[208:211], 0
	v_mfma_f32_16x16x32_bf16 v[92:95], v[130:133], v[222:225], 0
	v_mfma_f32_16x16x32_bf16 v[88:91], v[138:141], v[222:225], 0
	v_mfma_f32_16x16x32_bf16 v[76:79], v[130:133], v[230:233], 0
	v_mfma_f32_16x16x32_bf16 v[72:75], v[138:141], v[230:233], 0
	v_mfma_f32_16x16x32_bf16 v[124:127], v[134:137], v[204:207], v[124:127]
	v_mfma_f32_16x16x32_bf16 v[120:123], v[180:183], v[204:207], v[120:123]
	v_mfma_f32_16x16x32_bf16 v[108:111], v[134:137], v[218:221], v[108:111]
	v_mfma_f32_16x16x32_bf16 v[104:107], v[180:183], v[218:221], v[104:107]
	v_mfma_f32_16x16x32_bf16 v[92:95], v[134:137], v[226:229], v[92:95]
	v_mfma_f32_16x16x32_bf16 v[88:91], v[180:183], v[226:229], v[88:91]
	v_mfma_f32_16x16x32_bf16 v[76:79], v[134:137], v[234:237], v[76:79]
	v_mfma_f32_16x16x32_bf16 v[72:75], v[180:183], v[234:237], v[72:75]
	s_setprio 0
	s_setprio 1
	v_mfma_f32_16x16x32_bf16 v[116:119], v[184:187], v[200:203], 0
	v_mfma_f32_16x16x32_bf16 v[112:115], v[192:195], v[200:203], 0
	v_mfma_f32_16x16x32_bf16 v[100:103], v[184:187], v[208:211], 0
	v_mfma_f32_16x16x32_bf16 v[96:99], v[192:195], v[208:211], 0
	v_mfma_f32_16x16x32_bf16 v[84:87], v[184:187], v[222:225], 0
	v_mfma_f32_16x16x32_bf16 v[80:83], v[192:195], v[222:225], 0
	v_mfma_f32_16x16x32_bf16 v[68:71], v[184:187], v[230:233], 0
	v_mfma_f32_16x16x32_bf16 v[64:67], v[192:195], v[230:233], 0
	v_mfma_f32_16x16x32_bf16 v[116:119], v[188:191], v[204:207], v[116:119]
	v_mfma_f32_16x16x32_bf16 v[112:115], v[196:199], v[204:207], v[112:115]
	v_mfma_f32_16x16x32_bf16 v[100:103], v[188:191], v[218:221], v[100:103]
	v_mfma_f32_16x16x32_bf16 v[96:99], v[196:199], v[218:221], v[96:99]
	v_mfma_f32_16x16x32_bf16 v[84:87], v[188:191], v[226:229], v[84:87]
	v_mfma_f32_16x16x32_bf16 v[80:83], v[196:199], v[226:229], v[80:83]
	v_mfma_f32_16x16x32_bf16 v[68:71], v[188:191], v[234:237], v[68:71]
	v_mfma_f32_16x16x32_bf16 v[64:67], v[196:199], v[234:237], v[64:67]
	s_setprio 0
	s_barrier
	s_add_i32 s43, s43, s52
	s_mov_b64 s[100:101], s[84:85]
	s_mov_b32 m0, s43
	ds_read_b128 v[200:203], v167 offset:16384
	ds_read_b128 v[204:207], v167 offset:17408
	ds_read_b128 v[208:211], v167 offset:18432
	ds_read_b128 v[218:221], v167 offset:19456
	ds_read_b128 v[222:225], v167 offset:20480
	ds_read_b128 v[226:229], v167 offset:21504
	ds_read_b128 v[230:233], v167 offset:22528
	ds_read_b128 v[234:237], v167 offset:23552
	global_load_lds_dwordx4 v148, s[84:85]
	s_add_i32 m0, s43, 0x2000
	s_add_i32 s43, s99, s52
	global_load_lds_dwordx4 v152, s[84:85]
	s_add_u32 s84, s84, s74
	s_addc_u32 s85, s85, 0
	s_mov_b32 m0, s43
	s_nop 0
	global_load_lds_dwordx4 v148, s[84:85]
	s_add_i32 m0, s43, 0x2000
	s_nop 0
	global_load_lds_dwordx4 v152, s[84:85]
	s_mov_b32 m0, s53
	s_nop 0
	global_load_lds_dwordx4 v146, s[86:87]
	s_mov_b32 m0, s54
	s_nop 0
	global_load_lds_dwordx4 v150, s[86:87]
	s_waitcnt vmcnt(8)
	s_waitcnt lgkmcnt(0)
	s_barrier
	s_setprio 1
	v_mfma_f32_16x16x32_bf16 v[60:63], v[130:133], v[200:203], 0
	v_mfma_f32_16x16x32_bf16 v[56:59], v[138:141], v[200:203], 0
	v_mfma_f32_16x16x32_bf16 v[44:47], v[130:133], v[208:211], 0
	v_mfma_f32_16x16x32_bf16 v[40:43], v[138:141], v[208:211], 0
	v_mfma_f32_16x16x32_bf16 v[28:31], v[130:133], v[222:225], 0
	v_mfma_f32_16x16x32_bf16 v[24:27], v[138:141], v[222:225], 0
	v_mfma_f32_16x16x32_bf16 v[12:15], v[130:133], v[230:233], 0
	v_mfma_f32_16x16x32_bf16 v[8:11], v[138:141], v[230:233], 0
	v_mfma_f32_16x16x32_bf16 v[60:63], v[134:137], v[204:207], v[60:63]
	v_mfma_f32_16x16x32_bf16 v[56:59], v[180:183], v[204:207], v[56:59]
	v_mfma_f32_16x16x32_bf16 v[44:47], v[134:137], v[218:221], v[44:47]
	v_mfma_f32_16x16x32_bf16 v[40:43], v[180:183], v[218:221], v[40:43]
	v_mfma_f32_16x16x32_bf16 v[28:31], v[134:137], v[226:229], v[28:31]
	v_mfma_f32_16x16x32_bf16 v[24:27], v[180:183], v[226:229], v[24:27]
	v_mfma_f32_16x16x32_bf16 v[12:15], v[134:137], v[234:237], v[12:15]
	v_mfma_f32_16x16x32_bf16 v[8:11], v[180:183], v[234:237], v[8:11]
	s_setprio 0
	s_setprio 1
	v_mfma_f32_16x16x32_bf16 v[52:55], v[184:187], v[200:203], 0
	v_mfma_f32_16x16x32_bf16 v[48:51], v[192:195], v[200:203], 0
	v_mfma_f32_16x16x32_bf16 v[36:39], v[184:187], v[208:211], 0
	v_mfma_f32_16x16x32_bf16 v[32:35], v[192:195], v[208:211], 0
	v_mfma_f32_16x16x32_bf16 v[20:23], v[184:187], v[222:225], 0
	v_mfma_f32_16x16x32_bf16 v[16:19], v[192:195], v[222:225], 0
	v_mfma_f32_16x16x32_bf16 v[4:7], v[184:187], v[230:233], 0
	v_mfma_f32_16x16x32_bf16 v[0:3], v[192:195], v[230:233], 0
	v_mfma_f32_16x16x32_bf16 v[52:55], v[188:191], v[204:207], v[52:55]
	v_mfma_f32_16x16x32_bf16 v[48:51], v[196:199], v[204:207], v[48:51]
	v_mfma_f32_16x16x32_bf16 v[36:39], v[188:191], v[218:221], v[36:39]
	v_mfma_f32_16x16x32_bf16 v[32:35], v[196:199], v[218:221], v[32:35]
	v_mfma_f32_16x16x32_bf16 v[20:23], v[188:191], v[226:229], v[20:23]
	v_mfma_f32_16x16x32_bf16 v[16:19], v[196:199], v[226:229], v[16:19]
	v_mfma_f32_16x16x32_bf16 v[4:7], v[188:191], v[234:237], v[4:7]
	v_mfma_f32_16x16x32_bf16 v[0:3], v[196:199], v[234:237], v[0:3]
	s_setprio 0
	s_barrier
; #define PG8_STAGE(bufoff, gbase, voff) do { _Pragma("unroll") for (int _i = 0; _i < 2; ++_i) \
;         __builtin_amdgcn_global_load_lds((const unsigned*)((const char*)(gbase) + (voff)[_i]), (LAS unsigned*)(lds + (bufoff) + ldsw + _i * 8192), 16, 0, 0); } while (0)
; #define PG8_LDA(dst, b, h) do { _Pragma("unroll") for (int m = 0; m < 4; ++m) _Pragma("unroll") for (int k = 0; k < 2; ++k) dst[m][k] = *(const LAS bf16x8*)(lds + PG8_SA(b, h) + aoff + m * 2048 + k * 1024); } while (0)
; #define PG8_LDB(dst, b, h) do { _Pragma("unroll") for (int n = 0; n < 2; ++n) _Pragma("unroll") for (int k = 0; k < 2; ++k) dst[n][k] = *(const LAS bf16x8*)(lds + PG8_SB(b, h) + boff + n * 2048 + k * 1024); } while (0)
; #define PG8_MMA(ai, bj, At, Bt) do { __builtin_amdgcn_s_setprio(1); _Pragma("unroll") for (int m = 0; m < 4; ++m) _Pragma("unroll") for (int n = 0; n < 2; ++n) _Pragma("unroll") for (int k = 0; k < 2; ++k) \
;         acc[ai][bj][m][n] = __builtin_amdgcn_mfma_f32_16x16x32_bf16(Bt[n][k], At[m][k], acc[ai][bj][m][n], 0, 0, 0); __builtin_amdgcn_s_setprio(0); } while (0)
; #define PG8_WAIT_V(n) asm volatile("s_waitcnt vmcnt(" #n ")" ::: "memory")
; #define PG8_WAIT_L(n) asm volatile("s_waitcnt lgkmcnt(" #n ")" ::: "memory")
; #define PG8_BAR __builtin_amdgcn_s_barrier()
; #define PG8_SCHED __builtin_amdgcn_sched_barrier(0)
; __device__ __forceinline__ void gemm_phase(LAS unsigned char* lds, const GP p, const int tid) {
;     ...
;             PG8_LDB(B0, 1, 0); PG8_LDB(B1, 1, 1); PG8_SCHED; PG8_LDA(At, 1, 0); PG8_STAGE(PG8_SA(0, 1), a2 + hstep, voffA);
;             PG8_WAIT_V(8); PG8_WAIT_L(0); PG8_BAR; PG8_MMA(0, 0, At, B0); PG8_MMA(0, 1, At, B1); PG8_BAR; PG8_SCHED;
;             PG8_LDA(At, 1, 1); PG8_STAGE(PG8_SB(1, 0), b3, voffB); PG8_STAGE(PG8_SB(1, 1), b3 + hstep, voffB); PG8_STAGE(PG8_SA(1, 0), a3, voffA);
;             PG8_WAIT_V(8); PG8_WAIT_L(0); PG8_BAR; PG8_MMA(1, 0, At, B0); PG8_MMA(1, 1, At, B1); PG8_BAR; PG8_SCHED;
;         }
	s_add_i32 s43, 0, 0x18000
	s_add_i32 s99, 0, 0x1c000
	ds_read_b128 v[130:133], v240
	ds_read_b128 v[134:137], v240 offset:1024
	ds_read_b128 v[138:141], v240 offset:2048
	ds_read_b128 v[180:183], v240 offset:3072
	ds_read_b128 v[184:187], v241
	ds_read_b128 v[188:191], v241 offset:1024
	ds_read_b128 v[192:195], v241 offset:2048
	ds_read_b128 v[196:199], v241 offset:3072
	s_add_u32 s84, s86, s74
	s_addc_u32 s85, s87, 0
	s_mov_b32 m0, s55
	ds_read_b128 v[200:203], v167 offset:32768
	ds_read_b128 v[204:207], v167 offset:33792
	ds_read_b128 v[208:211], v167 offset:34816
	ds_read_b128 v[218:221], v167 offset:35840
	ds_read_b128 v[222:225], v167 offset:36864
	ds_read_b128 v[226:229], v167 offset:37888
	ds_read_b128 v[230:233], v167 offset:38912
	ds_read_b128 v[234:237], v167 offset:39936
	global_load_lds_dwordx4 v146, s[84:85]
	s_mov_b32 m0, s56
	s_nop 0
	global_load_lds_dwordx4 v150, s[84:85]
	s_waitcnt vmcnt(8)
	s_waitcnt lgkmcnt(0)
	s_barrier
	s_setprio 1
	v_mfma_f32_16x16x32_bf16 v[124:127], v[130:133], v[200:203], v[124:127]
	v_mfma_f32_16x16x32_bf16 v[120:123], v[138:141], v[200:203], v[120:123]
	v_mfma_f32_16x16x32_bf16 v[108:111], v[130:133], v[208:211], v[108:111]
	v_mfma_f32_16x16x32_bf16 v[104:107], v[138:141], v[208:211], v[104:107]
	v_mfma_f32_16x16x32_bf16 v[92:95], v[130:133], v[222:225], v[92:95]
	v_mfma_f32_16x16x32_bf16 v[88:91], v[138:141], v[222:225], v[88:91]
	v_mfma_f32_16x16x32_bf16 v[76:79], v[130:133], v[230:233], v[76:79]
	v_mfma_f32_16x16x32_bf16 v[72:75], v[138:141], v[230:233], v[72:75]
	v_mfma_f32_16x16x32_bf16 v[124:127], v[134:137], v[204:207], v[124:127]
	v_mfma_f32_16x16x32_bf16 v[120:123], v[180:183], v[204:207], v[120:123]
	v_mfma_f32_16x16x32_bf16 v[108:111], v[134:137], v[218:221], v[108:111]
	v_mfma_f32_16x16x32_bf16 v[104:107], v[180:183], v[218:221], v[104:107]
	v_mfma_f32_16x16x32_bf16 v[92:95], v[134:137], v[226:229], v[92:95]
	v_mfma_f32_16x16x32_bf16 v[88:91], v[180:183], v[226:229], v[88:91]
	v_mfma_f32_16x16x32_bf16 v[76:79], v[134:137], v[234:237], v[76:79]
	v_mfma_f32_16x16x32_bf16 v[72:75], v[180:183], v[234:237], v[72:75]
	s_setprio 0
	s_setprio 1
	v_mfma_f32_16x16x32_bf16 v[116:119], v[184:187], v[200:203], v[116:119]
	v_mfma_f32_16x16x32_bf16 v[112:115], v[192:195], v[200:203], v[112:115]
	v_mfma_f32_16x16x32_bf16 v[100:103], v[184:187], v[208:211], v[100:103]
	v_mfma_f32_16x16x32_bf16 v[96:99], v[192:195], v[208:211], v[96:99]
	v_mfma_f32_16x16x32_bf16 v[84:87], v[184:187], v[222:225], v[84:87]
	v_mfma_f32_16x16x32_bf16 v[80:83], v[192:195], v[222:225], v[80:83]
	v_mfma_f32_16x16x32_bf16 v[68:71], v[184:187], v[230:233], v[68:71]
	v_mfma_f32_16x16x32_bf16 v[64:67], v[192:195], v[230:233], v[64:67]
	v_mfma_f32_16x16x32_bf16 v[116:119], v[188:191], v[204:207], v[116:119]
	v_mfma_f32_16x16x32_bf16 v[112:115], v[196:199], v[204:207], v[112:115]
	v_mfma_f32_16x16x32_bf16 v[100:103], v[188:191], v[218:221], v[100:103]
	v_mfma_f32_16x16x32_bf16 v[96:99], v[196:199], v[218:221], v[96:99]
	v_mfma_f32_16x16x32_bf16 v[84:87], v[188:191], v[226:229], v[84:87]
	v_mfma_f32_16x16x32_bf16 v[80:83], v[196:199], v[226:229], v[80:83]
	v_mfma_f32_16x16x32_bf16 v[68:71], v[188:191], v[234:237], v[68:71]
	v_mfma_f32_16x16x32_bf16 v[64:67], v[196:199], v[234:237], v[64:67]
	s_setprio 0
	s_barrier
	s_add_i32 s43, s43, s52
	s_add_u32 s100, s100, 0x80
	s_addc_u32 s101, s101, 0
	s_mov_b32 m0, s43
	ds_read_b128 v[200:203], v167 offset:49152
	ds_read_b128 v[204:207], v167 offset:50176
	ds_read_b128 v[208:211], v167 offset:51200
	ds_read_b128 v[218:221], v167 offset:52224
	ds_read_b128 v[222:225], v167 offset:53248
	ds_read_b128 v[226:229], v167 offset:54272
	ds_read_b128 v[230:233], v167 offset:55296
	ds_read_b128 v[234:237], v167 offset:56320
	global_load_lds_dwordx4 v148, s[100:101]
	s_add_i32 m0, s43, 0x2000
	s_add_i32 s43, s99, s52
	global_load_lds_dwordx4 v152, s[100:101]
	s_add_u32 s100, s100, s74
	s_addc_u32 s101, s101, 0
	s_mov_b32 m0, s43
	s_nop 0
	global_load_lds_dwordx4 v148, s[100:101]
	s_add_u32 s86, s86, 0x80
	s_addc_u32 s87, s87, 0
	s_add_i32 m0, s43, 0x2000
	s_nop 0
	global_load_lds_dwordx4 v152, s[100:101]
	s_mov_b32 m0, s57
	s_nop 0
	global_load_lds_dwordx4 v146, s[86:87]
	s_mov_b32 m0, s58
	s_nop 0
	global_load_lds_dwordx4 v150, s[86:87]
	s_waitcnt vmcnt(8)
	s_waitcnt lgkmcnt(0)
	s_barrier
	s_setprio 1
	v_mfma_f32_16x16x32_bf16 v[60:63], v[130:133], v[200:203], v[60:63]
	v_mfma_f32_16x16x32_bf16 v[56:59], v[138:141], v[200:203], v[56:59]
	v_mfma_f32_16x16x32_bf16 v[44:47], v[130:133], v[208:211], v[44:47]
	v_mfma_f32_16x16x32_bf16 v[40:43], v[138:141], v[208:211], v[40:43]
	v_mfma_f32_16x16x32_bf16 v[28:31], v[130:133], v[222:225], v[28:31]
	v_mfma_f32_16x16x32_bf16 v[24:27], v[138:141], v[222:225], v[24:27]
	v_mfma_f32_16x16x32_bf16 v[12:15], v[130:133], v[230:233], v[12:15]
	v_mfma_f32_16x16x32_bf16 v[8:11], v[138:141], v[230:233], v[8:11]
	v_mfma_f32_16x16x32_bf16 v[60:63], v[134:137], v[204:207], v[60:63]
	v_mfma_f32_16x16x32_bf16 v[56:59], v[180:183], v[204:207], v[56:59]
	v_mfma_f32_16x16x32_bf16 v[44:47], v[134:137], v[218:221], v[44:47]
	v_mfma_f32_16x16x32_bf16 v[40:43], v[180:183], v[218:221], v[40:43]
	v_mfma_f32_16x16x32_bf16 v[28:31], v[134:137], v[226:229], v[28:31]
	v_mfma_f32_16x16x32_bf16 v[24:27], v[180:183], v[226:229], v[24:27]
	v_mfma_f32_16x16x32_bf16 v[12:15], v[134:137], v[234:237], v[12:15]
	v_mfma_f32_16x16x32_bf16 v[8:11], v[180:183], v[234:237], v[8:11]
	s_setprio 0
	s_setprio 1
	v_mfma_f32_16x16x32_bf16 v[52:55], v[184:187], v[200:203], v[52:55]
	v_mfma_f32_16x16x32_bf16 v[48:51], v[192:195], v[200:203], v[48:51]
	v_mfma_f32_16x16x32_bf16 v[36:39], v[184:187], v[208:211], v[36:39]
	v_mfma_f32_16x16x32_bf16 v[32:35], v[192:195], v[208:211], v[32:35]
	v_mfma_f32_16x16x32_bf16 v[20:23], v[184:187], v[222:225], v[20:23]
	v_mfma_f32_16x16x32_bf16 v[16:19], v[192:195], v[222:225], v[16:19]
	v_mfma_f32_16x16x32_bf16 v[4:7], v[184:187], v[230:233], v[4:7]
	v_mfma_f32_16x16x32_bf16 v[0:3], v[192:195], v[230:233], v[0:3]
	v_mfma_f32_16x16x32_bf16 v[52:55], v[188:191], v[204:207], v[52:55]
	v_mfma_f32_16x16x32_bf16 v[48:51], v[196:199], v[204:207], v[48:51]
	v_mfma_f32_16x16x32_bf16 v[36:39], v[188:191], v[218:221], v[36:39]
	v_mfma_f32_16x16x32_bf16 v[32:35], v[196:199], v[218:221], v[32:35]
	v_mfma_f32_16x16x32_bf16 v[20:23], v[188:191], v[226:229], v[20:23]
	v_mfma_f32_16x16x32_bf16 v[16:19], v[196:199], v[226:229], v[16:19]
	v_mfma_f32_16x16x32_bf16 v[4:7], v[188:191], v[234:237], v[4:7]
	v_mfma_f32_16x16x32_bf16 v[0:3], v[196:199], v[234:237], v[0:3]
	s_setprio 0
	s_barrier
	s_add_u32 s82, s82, 0x100
	s_addc_u32 s83, s83, 0
	s_add_u32 s81, s81, 0x100
	s_addc_u32 s91, s91, 0
	s_cmp_ge_u32 s98, s60
	s_cbranch_scc1 .LBB0_107
	s_branch .LBB0_105
; #define PG8_STAGE(bufoff, gbase, voff) do { _Pragma("unroll") for (int _i = 0; _i < 2; ++_i) \
;         __builtin_amdgcn_global_load_lds((const unsigned*)((const char*)(gbase) + (voff)[_i]), (LAS unsigned*)(lds + (bufoff) + ldsw + _i * 8192), 16, 0, 0); } while (0)
; #define PG8_LDA(dst, b, h) do { _Pragma("unroll") for (int m = 0; m < 4; ++m) _Pragma("unroll") for (int k = 0; k < 2; ++k) dst[m][k] = *(const LAS bf16x8*)(lds + PG8_SA(b, h) + aoff + m * 2048 + k * 1024); } while (0)
; #define PG8_LDB(dst, b, h) do { _Pragma("unroll") for (int n = 0; n < 2; ++n) _Pragma("unroll") for (int k = 0; k < 2; ++k) dst[n][k] = *(const LAS bf16x8*)(lds + PG8_SB(b, h) + boff + n * 2048 + k * 1024); } while (0)
; #define PG8_MMA(ai, bj, At, Bt) do { __builtin_amdgcn_s_setprio(1); _Pragma("unroll") for (int m = 0; m < 4; ++m) _Pragma("unroll") for (int n = 0; n < 2; ++n) _Pragma("unroll") for (int k = 0; k < 2; ++k) \
;         acc[ai][bj][m][n] = __builtin_amdgcn_mfma_f32_16x16x32_bf16(Bt[n][k], At[m][k], acc[ai][bj][m][n], 0, 0, 0); __builtin_amdgcn_s_setprio(0); } while (0)
; #define PG8_BAR __builtin_amdgcn_s_barrier()
; __device__ __forceinline__ void gemm_phase(LAS unsigned char* lds, const GP p, const int tid) {
;     ...
;         for (int t = 0; t < nt; t += 2) {
;             const bool last = (t == nt - 2);
;             if (last && p.mode != 1) {
;                 const float* rp = p.rs + cur.pm * BM + wr * 64 + fr;
; #pragma unroll
;                 for (int ai = 0; ai < 2; ++ai)
; #pragma unroll
;                     for (int m = 0; m < 4; ++m) rsv[ai][m] = rp[ai * HALF + m * 16];
;             }
;             const char* a1 = cA + (size_t)(t + 1) * kstep;
;             const char* a2 = last ? nA : cA + (size_t)(t + 2) * kstep; const char* b2 = last ? nB : cB + (size_t)(t + 2) * kstep;
;             const char* a3 = a2 + kstep; const char* b3 = b2 + kstep;
;             PG8_LDB(B0, 0, 0); PG8_LDB(B1, 0, 1); PG8_SCHED; PG8_LDA(At, 0, 0); PG8_STAGE(PG8_SA(1, 1), a1 + hstep, voffA);
;             PG8_WAIT_V(8); PG8_WAIT_L(0); PG8_BAR; PG8_MMA(0, 0, At, B0); PG8_MMA(0, 1, At, B1); PG8_BAR; PG8_SCHED;
;             PG8_LDA(At, 0, 1); PG8_STAGE(PG8_SB(0, 0), b2, voffB); PG8_STAGE(PG8_SB(0, 1), b2 + hstep, voffB); PG8_STAGE(PG8_SA(0, 0), a2, voffA);
;             PG8_WAIT_V(8); PG8_WAIT_L(0); PG8_BAR; PG8_MMA(1, 0, At, B0); PG8_MMA(1, 1, At, B1); PG8_BAR; PG8_SCHED;
.LBB0_104:
	s_cmp_eq_u32 s98, 0
	s_cbranch_scc1 .Lpeel_body
	s_add_i32 s98, s98, 2
	s_add_u32 s43, s82, 0x80
	s_addc_u32 s99, s83, 0
	s_and_b64 s[86:87], s[84:85], exec
	s_cselect_b32 s87, s77, s99
	s_cselect_b32 s86, s76, s43
	s_add_i32 s43, 0, 0x10000
	s_and_b64 s[84:85], s[84:85], exec
	s_cselect_b32 s85, s79, s91
	s_cselect_b32 s84, s78, s81
	s_add_i32 s99, 0, 0x14000
	ds_read_b128 v[130:133], v238
	ds_read_b128 v[134:137], v238 offset:1024
	ds_read_b128 v[138:141], v238 offset:2048
	ds_read_b128 v[180:183], v238 offset:3072
	ds_read_b128 v[184:187], v239
	ds_read_b128 v[188:191], v239 offset:1024
	ds_read_b128 v[192:195], v239 offset:2048
	ds_read_b128 v[196:199], v239 offset:3072
	s_add_i32 m0, s53, 0xc000
	ds_read_b128 v[200:203], v167
	ds_read_b128 v[204:207], v167 offset:1024
	ds_read_b128 v[208:211], v167 offset:2048
	ds_read_b128 v[218:221], v167 offset:3072
	ds_read_b128 v[222:225], v167 offset:4096
	ds_read_b128 v[226:229], v167 offset:5120
	ds_read_b128 v[230:233], v167 offset:6144
	ds_read_b128 v[234:237], v167 offset:7168
	global_load_lds_dwordx4 v160, s[82:83]
	s_add_i32 m0, s53, 0xe000
	s_nop 0
	global_load_lds_dwordx4 v162, s[82:83]
	s_waitcnt vmcnt(8)
	s_waitcnt lgkmcnt(0)
	s_barrier
	s_setprio 1
	v_mfma_f32_16x16x32_bf16 v[124:127], v[130:133], v[200:203], v[124:127]
	v_mfma_f32_16x16x32_bf16 v[120:123], v[138:141], v[200:203], v[120:123]
	v_mfma_f32_16x16x32_bf16 v[108:111], v[130:133], v[208:211], v[108:111]
	v_mfma_f32_16x16x32_bf16 v[104:107], v[138:141], v[208:211], v[104:107]
	v_mfma_f32_16x16x32_bf16 v[92:95], v[130:133], v[222:225], v[92:95]
	v_mfma_f32_16x16x32_bf16 v[88:91], v[138:141], v[222:225], v[88:91]
	v_mfma_f32_16x16x32_bf16 v[76:79], v[130:133], v[230:233], v[76:79]
	v_mfma_f32_16x16x32_bf16 v[72:75], v[138:141], v[230:233], v[72:75]
	v_mfma_f32_16x16x32_bf16 v[124:127], v[134:137], v[204:207], v[124:127]
	v_mfma_f32_16x16x32_bf16 v[120:123], v[180:183], v[204:207], v[120:123]
	v_mfma_f32_16x16x32_bf16 v[108:111], v[134:137], v[218:221], v[108:111]
	v_mfma_f32_16x16x32_bf16 v[104:107], v[180:183], v[218:221], v[104:107]
	v_mfma_f32_16x16x32_bf16 v[92:95], v[134:137], v[226:229], v[92:95]
	v_mfma_f32_16x16x32_bf16 v[88:91], v[180:183], v[226:229], v[88:91]
	v_mfma_f32_16x16x32_bf16 v[76:79], v[134:137], v[234:237], v[76:79]
	v_mfma_f32_16x16x32_bf16 v[72:75], v[180:183], v[234:237], v[72:75]
	s_setprio 0
	s_setprio 1
	v_mfma_f32_16x16x32_bf16 v[116:119], v[184:187], v[200:203], v[116:119]
	v_mfma_f32_16x16x32_bf16 v[112:115], v[192:195], v[200:203], v[112:115]
	v_mfma_f32_16x16x32_bf16 v[100:103], v[184:187], v[208:211], v[100:103]
	v_mfma_f32_16x16x32_bf16 v[96:99], v[192:195], v[208:211], v[96:99]
	v_mfma_f32_16x16x32_bf16 v[84:87], v[184:187], v[222:225], v[84:87]
	v_mfma_f32_16x16x32_bf16 v[80:83], v[192:195], v[222:225], v[80:83]
	v_mfma_f32_16x16x32_bf16 v[68:71], v[184:187], v[230:233], v[68:71]
	v_mfma_f32_16x16x32_bf16 v[64:67], v[192:195], v[230:233], v[64:67]
	v_mfma_f32_16x16x32_bf16 v[116:119], v[188:191], v[204:207], v[116:119]
	v_mfma_f32_16x16x32_bf16 v[112:115], v[196:199], v[204:207], v[112:115]
	v_mfma_f32_16x16x32_bf16 v[100:103], v[188:191], v[218:221], v[100:103]
	v_mfma_f32_16x16x32_bf16 v[96:99], v[196:199], v[218:221], v[96:99]
	v_mfma_f32_16x16x32_bf16 v[84:87], v[188:191], v[226:229], v[84:87]
	v_mfma_f32_16x16x32_bf16 v[80:83], v[196:199], v[226:229], v[80:83]
	v_mfma_f32_16x16x32_bf16 v[68:71], v[188:191], v[234:237], v[68:71]
	v_mfma_f32_16x16x32_bf16 v[64:67], v[196:199], v[234:237], v[64:67]
	s_setprio 0
	s_barrier
	s_add_i32 s43, s43, s52
	s_mov_b64 s[100:101], s[84:85]
	s_mov_b32 m0, s43
	ds_read_b128 v[200:203], v167 offset:16384
	ds_read_b128 v[204:207], v167 offset:17408
	ds_read_b128 v[208:211], v167 offset:18432
	ds_read_b128 v[218:221], v167 offset:19456
	ds_read_b128 v[222:225], v167 offset:20480
	ds_read_b128 v[226:229], v167 offset:21504
	ds_read_b128 v[230:233], v167 offset:22528
	ds_read_b128 v[234:237], v167 offset:23552
	global_load_lds_dwordx4 v148, s[84:85]
	s_add_i32 m0, s43, 0x2000
	s_add_i32 s43, s99, s52
	global_load_lds_dwordx4 v152, s[84:85]
	s_add_u32 s84, s84, s74
	s_addc_u32 s85, s85, 0
	s_mov_b32 m0, s43
	s_nop 0
	global_load_lds_dwordx4 v148, s[84:85]
	s_add_i32 m0, s43, 0x2000
	s_nop 0
	global_load_lds_dwordx4 v152, s[84:85]
	s_mov_b32 m0, s53
	s_nop 0
	global_load_lds_dwordx4 v146, s[86:87]
	s_mov_b32 m0, s54
	s_nop 0
	global_load_lds_dwordx4 v150, s[86:87]
	s_waitcnt vmcnt(8)
	s_waitcnt lgkmcnt(0)
	s_barrier
	s_setprio 1
	v_mfma_f32_16x16x32_bf16 v[60:63], v[130:133], v[200:203], v[60:63]
	v_mfma_f32_16x16x32_bf16 v[56:59], v[138:141], v[200:203], v[56:59]
	v_mfma_f32_16x16x32_bf16 v[44:47], v[130:133], v[208:211], v[44:47]
	v_mfma_f32_16x16x32_bf16 v[40:43], v[138:141], v[208:211], v[40:43]
	v_mfma_f32_16x16x32_bf16 v[28:31], v[130:133], v[222:225], v[28:31]
	v_mfma_f32_16x16x32_bf16 v[24:27], v[138:141], v[222:225], v[24:27]
	v_mfma_f32_16x16x32_bf16 v[12:15], v[130:133], v[230:233], v[12:15]
	v_mfma_f32_16x16x32_bf16 v[8:11], v[138:141], v[230:233], v[8:11]
	v_mfma_f32_16x16x32_bf16 v[60:63], v[134:137], v[204:207], v[60:63]
	v_mfma_f32_16x16x32_bf16 v[56:59], v[180:183], v[204:207], v[56:59]
	v_mfma_f32_16x16x32_bf16 v[44:47], v[134:137], v[218:221], v[44:47]
	v_mfma_f32_16x16x32_bf16 v[40:43], v[180:183], v[218:221], v[40:43]
	v_mfma_f32_16x16x32_bf16 v[28:31], v[134:137], v[226:229], v[28:31]
	v_mfma_f32_16x16x32_bf16 v[24:27], v[180:183], v[226:229], v[24:27]
	v_mfma_f32_16x16x32_bf16 v[12:15], v[134:137], v[234:237], v[12:15]
	v_mfma_f32_16x16x32_bf16 v[8:11], v[180:183], v[234:237], v[8:11]
	s_setprio 0
	s_setprio 1
	v_mfma_f32_16x16x32_bf16 v[52:55], v[184:187], v[200:203], v[52:55]
	v_mfma_f32_16x16x32_bf16 v[48:51], v[192:195], v[200:203], v[48:51]
	v_mfma_f32_16x16x32_bf16 v[36:39], v[184:187], v[208:211], v[36:39]
	v_mfma_f32_16x16x32_bf16 v[32:35], v[192:195], v[208:211], v[32:35]
	v_mfma_f32_16x16x32_bf16 v[20:23], v[184:187], v[222:225], v[20:23]
	v_mfma_f32_16x16x32_bf16 v[16:19], v[192:195], v[222:225], v[16:19]
	v_mfma_f32_16x16x32_bf16 v[4:7], v[184:187], v[230:233], v[4:7]
	v_mfma_f32_16x16x32_bf16 v[0:3], v[192:195], v[230:233], v[0:3]
	v_mfma_f32_16x16x32_bf16 v[52:55], v[188:191], v[204:207], v[52:55]
	v_mfma_f32_16x16x32_bf16 v[48:51], v[196:199], v[204:207], v[48:51]
	v_mfma_f32_16x16x32_bf16 v[36:39], v[188:191], v[218:221], v[36:39]
	v_mfma_f32_16x16x32_bf16 v[32:35], v[196:199], v[218:221], v[32:35]
	v_mfma_f32_16x16x32_bf16 v[20:23], v[188:191], v[226:229], v[20:23]
	v_mfma_f32_16x16x32_bf16 v[16:19], v[196:199], v[226:229], v[16:19]
	v_mfma_f32_16x16x32_bf16 v[4:7], v[188:191], v[234:237], v[4:7]
	v_mfma_f32_16x16x32_bf16 v[0:3], v[196:199], v[234:237], v[0:3]
	s_setprio 0
	s_barrier
; #define PG8_STAGE(bufoff, gbase, voff) do { _Pragma("unroll") for (int _i = 0; _i < 2; ++_i) \
;         __builtin_amdgcn_global_load_lds((const unsigned*)((const char*)(gbase) + (voff)[_i]), (LAS unsigned*)(lds + (bufoff) + ldsw + _i * 8192), 16, 0, 0); } while (0)
; #define PG8_LDA(dst, b, h) do { _Pragma("unroll") for (int m = 0; m < 4; ++m) _Pragma("unroll") for (int k = 0; k < 2; ++k) dst[m][k] = *(const LAS bf16x8*)(lds + PG8_SA(b, h) + aoff + m * 2048 + k * 1024); } while (0)
; #define PG8_LDB(dst, b, h) do { _Pragma("unroll") for (int n = 0; n < 2; ++n) _Pragma("unroll") for (int k = 0; k < 2; ++k) dst[n][k] = *(const LAS bf16x8*)(lds + PG8_SB(b, h) + boff + n * 2048 + k * 1024); } while (0)
; #define PG8_MMA(ai, bj, At, Bt) do { __builtin_amdgcn_s_setprio(1); _Pragma("unroll") for (int m = 0; m < 4; ++m) _Pragma("unroll") for (int n = 0; n < 2; ++n) _Pragma("unroll") for (int k = 0; k < 2; ++k) \
;         acc[ai][bj][m][n] = __builtin_amdgcn_mfma_f32_16x16x32_bf16(Bt[n][k], At[m][k], acc[ai][bj][m][n], 0, 0, 0); __builtin_amdgcn_s_setprio(0); } while (0)
; #define PG8_WAIT_V(n) asm volatile("s_waitcnt vmcnt(" #n ")" ::: "memory")
; #define PG8_WAIT_L(n) asm volatile("s_waitcnt lgkmcnt(" #n ")" ::: "memory")
; #define PG8_BAR __builtin_amdgcn_s_barrier()
; #define PG8_SCHED __builtin_amdgcn_sched_barrier(0)
; __device__ __forceinline__ void gemm_phase(LAS unsigned char* lds, const GP p, const int tid) {
;     ...
;             PG8_LDB(B0, 1, 0); PG8_LDB(B1, 1, 1); PG8_SCHED; PG8_LDA(At, 1, 0); PG8_STAGE(PG8_SA(0, 1), a2 + hstep, voffA);
;             PG8_WAIT_V(8); PG8_WAIT_L(0); PG8_BAR; PG8_MMA(0, 0, At, B0); PG8_MMA(0, 1, At, B1); PG8_BAR; PG8_SCHED;
;             PG8_LDA(At, 1, 1); PG8_STAGE(PG8_SB(1, 0), b3, voffB); PG8_STAGE(PG8_SB(1, 1), b3 + hstep, voffB); PG8_STAGE(PG8_SA(1, 0), a3, voffA);
;             PG8_WAIT_V(8); PG8_WAIT_L(0); PG8_BAR; PG8_MMA(1, 0, At, B0); PG8_MMA(1, 1, At, B1); PG8_BAR; PG8_SCHED;
;         }
	s_add_i32 s43, 0, 0x18000
	s_add_i32 s99, 0, 0x1c000
	ds_read_b128 v[130:133], v240
	ds_read_b128 v[134:137], v240 offset:1024
	ds_read_b128 v[138:141], v240 offset:2048
	ds_read_b128 v[180:183], v240 offset:3072
	ds_read_b128 v[184:187], v241
	ds_read_b128 v[188:191], v241 offset:1024
	ds_read_b128 v[192:195], v241 offset:2048
	ds_read_b128 v[196:199], v241 offset:3072
	s_add_u32 s84, s86, s74
	s_addc_u32 s85, s87, 0
	s_mov_b32 m0, s55
	ds_read_b128 v[200:203], v167 offset:32768
	ds_read_b128 v[204:207], v167 offset:33792
	ds_read_b128 v[208:211], v167 offset:34816
	ds_read_b128 v[218:221], v167 offset:35840
	ds_read_b128 v[222:225], v167 offset:36864
	ds_read_b128 v[226:229], v167 offset:37888
	ds_read_b128 v[230:233], v167 offset:38912
	ds_read_b128 v[234:237], v167 offset:39936
	global_load_lds_dwordx4 v146, s[84:85]
	s_mov_b32 m0, s56
	s_nop 0
	global_load_lds_dwordx4 v150, s[84:85]
	s_waitcnt vmcnt(8)
	s_waitcnt lgkmcnt(0)
	s_barrier
	s_setprio 1
	v_mfma_f32_16x16x32_bf16 v[124:127], v[130:133], v[200:203], v[124:127]
	v_mfma_f32_16x16x32_bf16 v[120:123], v[138:141], v[200:203], v[120:123]
	v_mfma_f32_16x16x32_bf16 v[108:111], v[130:133], v[208:211], v[108:111]
	v_mfma_f32_16x16x32_bf16 v[104:107], v[138:141], v[208:211], v[104:107]
	v_mfma_f32_16x16x32_bf16 v[92:95], v[130:133], v[222:225], v[92:95]
	v_mfma_f32_16x16x32_bf16 v[88:91], v[138:141], v[222:225], v[88:91]
	v_mfma_f32_16x16x32_bf16 v[76:79], v[130:133], v[230:233], v[76:79]
	v_mfma_f32_16x16x32_bf16 v[72:75], v[138:141], v[230:233], v[72:75]
	v_mfma_f32_16x16x32_bf16 v[124:127], v[134:137], v[204:207], v[124:127]
	v_mfma_f32_16x16x32_bf16 v[120:123], v[180:183], v[204:207], v[120:123]
	v_mfma_f32_16x16x32_bf16 v[108:111], v[134:137], v[218:221], v[108:111]
	v_mfma_f32_16x16x32_bf16 v[104:107], v[180:183], v[218:221], v[104:107]
	v_mfma_f32_16x16x32_bf16 v[92:95], v[134:137], v[226:229], v[92:95]
	v_mfma_f32_16x16x32_bf16 v[88:91], v[180:183], v[226:229], v[88:91]
	v_mfma_f32_16x16x32_bf16 v[76:79], v[134:137], v[234:237], v[76:79]
	v_mfma_f32_16x16x32_bf16 v[72:75], v[180:183], v[234:237], v[72:75]
	s_setprio 0
	s_setprio 1
	v_mfma_f32_16x16x32_bf16 v[116:119], v[184:187], v[200:203], v[116:119]
	v_mfma_f32_16x16x32_bf16 v[112:115], v[192:195], v[200:203], v[112:115]
	v_mfma_f32_16x16x32_bf16 v[100:103], v[184:187], v[208:211], v[100:103]
	v_mfma_f32_16x16x32_bf16 v[96:99], v[192:195], v[208:211], v[96:99]
	v_mfma_f32_16x16x32_bf16 v[84:87], v[184:187], v[222:225], v[84:87]
	v_mfma_f32_16x16x32_bf16 v[80:83], v[192:195], v[222:225], v[80:83]
	v_mfma_f32_16x16x32_bf16 v[68:71], v[184:187], v[230:233], v[68:71]
	v_mfma_f32_16x16x32_bf16 v[64:67], v[192:195], v[230:233], v[64:67]
	v_mfma_f32_16x16x32_bf16 v[116:119], v[188:191], v[204:207], v[116:119]
	v_mfma_f32_16x16x32_bf16 v[112:115], v[196:199], v[204:207], v[112:115]
	v_mfma_f32_16x16x32_bf16 v[100:103], v[188:191], v[218:221], v[100:103]
	v_mfma_f32_16x16x32_bf16 v[96:99], v[196:199], v[218:221], v[96:99]
	v_mfma_f32_16x16x32_bf16 v[84:87], v[188:191], v[226:229], v[84:87]
	v_mfma_f32_16x16x32_bf16 v[80:83], v[196:199], v[226:229], v[80:83]
	v_mfma_f32_16x16x32_bf16 v[68:71], v[188:191], v[234:237], v[68:71]
	v_mfma_f32_16x16x32_bf16 v[64:67], v[196:199], v[234:237], v[64:67]
	s_setprio 0
	s_barrier
	s_add_i32 s43, s43, s52
	s_add_u32 s100, s100, 0x80
	s_addc_u32 s101, s101, 0
	s_mov_b32 m0, s43
	ds_read_b128 v[200:203], v167 offset:49152
	ds_read_b128 v[204:207], v167 offset:50176
	ds_read_b128 v[208:211], v167 offset:51200
	ds_read_b128 v[218:221], v167 offset:52224
	ds_read_b128 v[222:225], v167 offset:53248
	ds_read_b128 v[226:229], v167 offset:54272
	ds_read_b128 v[230:233], v167 offset:55296
	ds_read_b128 v[234:237], v167 offset:56320
	global_load_lds_dwordx4 v148, s[100:101]
	s_add_i32 m0, s43, 0x2000
	s_add_i32 s43, s99, s52
	global_load_lds_dwordx4 v152, s[100:101]
	s_add_u32 s100, s100, s74
	s_addc_u32 s101, s101, 0
	s_mov_b32 m0, s43
	s_nop 0
	global_load_lds_dwordx4 v148, s[100:101]
	s_add_u32 s86, s86, 0x80
	s_addc_u32 s87, s87, 0
	s_add_i32 m0, s43, 0x2000
	s_nop 0
	global_load_lds_dwordx4 v152, s[100:101]
	s_mov_b32 m0, s57
	s_nop 0
	global_load_lds_dwordx4 v146, s[86:87]
	s_mov_b32 m0, s58
	s_nop 0
	global_load_lds_dwordx4 v150, s[86:87]
	s_waitcnt vmcnt(8)
	s_waitcnt lgkmcnt(0)
	s_barrier
	s_setprio 1
	v_mfma_f32_16x16x32_bf16 v[60:63], v[130:133], v[200:203], v[60:63]
	v_mfma_f32_16x16x32_bf16 v[56:59], v[138:141], v[200:203], v[56:59]
	v_mfma_f32_16x16x32_bf16 v[44:47], v[130:133], v[208:211], v[44:47]
	v_mfma_f32_16x16x32_bf16 v[40:43], v[138:141], v[208:211], v[40:43]
	v_mfma_f32_16x16x32_bf16 v[28:31], v[130:133], v[222:225], v[28:31]
	v_mfma_f32_16x16x32_bf16 v[24:27], v[138:141], v[222:225], v[24:27]
	v_mfma_f32_16x16x32_bf16 v[12:15], v[130:133], v[230:233], v[12:15]
	v_mfma_f32_16x16x32_bf16 v[8:11], v[138:141], v[230:233], v[8:11]
	v_mfma_f32_16x16x32_bf16 v[60:63], v[134:137], v[204:207], v[60:63]
	v_mfma_f32_16x16x32_bf16 v[56:59], v[180:183], v[204:207], v[56:59]
	v_mfma_f32_16x16x32_bf16 v[44:47], v[134:137], v[218:221], v[44:47]
	v_mfma_f32_16x16x32_bf16 v[40:43], v[180:183], v[218:221], v[40:43]
	v_mfma_f32_16x16x32_bf16 v[28:31], v[134:137], v[226:229], v[28:31]
	v_mfma_f32_16x16x32_bf16 v[24:27], v[180:183], v[226:229], v[24:27]
	v_mfma_f32_16x16x32_bf16 v[12:15], v[134:137], v[234:237], v[12:15]
	v_mfma_f32_16x16x32_bf16 v[8:11], v[180:183], v[234:237], v[8:11]
	s_setprio 0
	s_setprio 1
	v_mfma_f32_16x16x32_bf16 v[52:55], v[184:187], v[200:203], v[52:55]
	v_mfma_f32_16x16x32_bf16 v[48:51], v[192:195], v[200:203], v[48:51]
	v_mfma_f32_16x16x32_bf16 v[36:39], v[184:187], v[208:211], v[36:39]
	v_mfma_f32_16x16x32_bf16 v[32:35], v[192:195], v[208:211], v[32:35]
	v_mfma_f32_16x16x32_bf16 v[20:23], v[184:187], v[222:225], v[20:23]
	v_mfma_f32_16x16x32_bf16 v[16:19], v[192:195], v[222:225], v[16:19]
	v_mfma_f32_16x16x32_bf16 v[4:7], v[184:187], v[230:233], v[4:7]
	v_mfma_f32_16x16x32_bf16 v[0:3], v[192:195], v[230:233], v[0:3]
	v_mfma_f32_16x16x32_bf16 v[52:55], v[188:191], v[204:207], v[52:55]
	v_mfma_f32_16x16x32_bf16 v[48:51], v[196:199], v[204:207], v[48:51]
	v_mfma_f32_16x16x32_bf16 v[36:39], v[188:191], v[218:221], v[36:39]
	v_mfma_f32_16x16x32_bf16 v[32:35], v[196:199], v[218:221], v[32:35]
	v_mfma_f32_16x16x32_bf16 v[20:23], v[188:191], v[226:229], v[20:23]
	v_mfma_f32_16x16x32_bf16 v[16:19], v[196:199], v[226:229], v[16:19]
	v_mfma_f32_16x16x32_bf16 v[4:7], v[188:191], v[234:237], v[4:7]
	v_mfma_f32_16x16x32_bf16 v[0:3], v[196:199], v[234:237], v[0:3]
	s_setprio 0
	s_barrier
	s_add_u32 s82, s82, 0x100
	s_addc_u32 s83, s83, 0
	s_add_u32 s81, s81, 0x100
	s_addc_u32 s91, s91, 0
	s_cmp_ge_u32 s98, s60
	s_cbranch_scc1 .LBB0_107
